# SwiGLU epilogue rewritten by hand: packed f32 mul/add (same per-element operation order), running store address instead of a 64-bit multiply per store
# speedup vs baseline: 1.0072x; 1.0072x over previous
; __device__ __forceinline__ unsigned cvt_pk_bf16(float lo, float hi) { unsigned r; asm volatile("v_cvt_pk_bf16_f32 %0, %1, %2" : "=v"(r) : "v"(lo), "v"(hi)); return r; }
;     static __device__ __forceinline__ float sw(float g, float up) { return g * __builtin_amdgcn_rcpf(1.0f + __builtin_amdgcn_exp2f(-1.4426950408889634f * g)) * up; }
;     __device__ __forceinline__ void operator()(const f32x4 (&acc)[2][2][4][2], const Unit& u, int wr, int wc, int fr, int fq) const {
;         const int row0 = u.pm * BM + wr * 64 + fr, col0 = u.pn * HALF + wc * 32 + 8 * fq;
; #pragma unroll
;         for (int ai = 0; ai < 2; ++ai)
; #pragma unroll
;             for (int m = 0; m < 4; ++m) { bf16_t* rowp = Hout + (size_t)(row0 + ai * HALF + m * 16) * ldc + col0;
;                 const f32x4 g0 = acc[ai][0][m][0], g1 = acc[ai][0][m][1], u0 = acc[ai][1][m][0], u1 = acc[ai][1][m][1];
;                 u32x4 w; w.x = cvt_pk_bf16(sw(g0[0], u0[0]), sw(g0[1], u0[1])); w.y = cvt_pk_bf16(sw(g0[2], u0[2]), sw(g0[3], u0[3]));
;                 w.z = cvt_pk_bf16(sw(g1[0], u1[0]), sw(g1[1], u1[1])); w.w = cvt_pk_bf16(sw(g1[2], u1[2]), sw(g1[3], u1[3]));
;                 *(u32x4*)rowp = w; }
.LBB0_327:
	s_cmp_lg_u32 s57, 1
	v_mul_lo_u32 v132, s45, v170
	s_cbranch_scc0 .LBB0_329
	v_lshl_or_b32 v130, s73, 7, v200
	v_ashrrev_i32_e32 v133, 31, v170
	v_ashrrev_i32_e32 v131, 31, v130
	v_mul_lo_u32 v133, s44, v133
	v_mad_u64_u32 v[134:135], s[12:13], s44, v170, 0
	v_lshl_add_u64 v[130:131], v[130:131], 1, s[8:9]
	v_add3_u32 v135, v135, v133, v132
	v_lshl_add_u64 v[138:139], v[134:135], 1, v[130:131]
	s_mov_b32 s14, 0xbfb8aa3b
	s_mov_b32 s15, 0
	s_mov_b32 s42, 1.0
	s_mov_b32 s43, 0
	s_mov_b32 s16, 0x2c000
	s_mov_b32 s17, 0
	v_pk_mul_f32 v[202:203], v[126:127], s[14:15] op_sel_hi:[1,0]
	v_pk_mul_f32 v[204:205], v[128:129], s[14:15] op_sel_hi:[1,0]
	v_pk_mul_f32 v[206:207], v[122:123], s[14:15] op_sel_hi:[1,0]
	v_pk_mul_f32 v[208:209], v[124:125], s[14:15] op_sel_hi:[1,0]
	v_exp_f32_e32 v202, v202
	v_exp_f32_e32 v203, v203
	v_exp_f32_e32 v204, v204
	v_exp_f32_e32 v205, v205
	v_exp_f32_e32 v206, v206
	v_exp_f32_e32 v207, v207
	v_exp_f32_e32 v208, v208
	v_exp_f32_e32 v209, v209
	v_pk_add_f32 v[202:203], v[202:203], s[42:43] op_sel_hi:[1,0]
	v_pk_add_f32 v[204:205], v[204:205], s[42:43] op_sel_hi:[1,0]
	v_pk_add_f32 v[206:207], v[206:207], s[42:43] op_sel_hi:[1,0]
	v_pk_add_f32 v[208:209], v[208:209], s[42:43] op_sel_hi:[1,0]
	v_rcp_f32_e32 v202, v202
	v_rcp_f32_e32 v203, v203
	v_rcp_f32_e32 v204, v204
	v_rcp_f32_e32 v205, v205
	v_rcp_f32_e32 v206, v206
	v_rcp_f32_e32 v207, v207
	v_rcp_f32_e32 v208, v208
	v_rcp_f32_e32 v209, v209
	v_pk_mul_f32 v[202:203], v[126:127], v[202:203]
	v_pk_mul_f32 v[204:205], v[128:129], v[204:205]
	v_pk_mul_f32 v[206:207], v[122:123], v[206:207]
	v_pk_mul_f32 v[208:209], v[124:125], v[208:209]
	v_pk_mul_f32 v[202:203], v[202:203], v[118:119]
	v_pk_mul_f32 v[204:205], v[204:205], v[120:121]
	v_pk_mul_f32 v[206:207], v[206:207], v[114:115]
	v_pk_mul_f32 v[208:209], v[208:209], v[116:117]
	v_cvt_pk_bf16_f32 v210, v202, v203
	v_cvt_pk_bf16_f32 v211, v204, v205
	v_cvt_pk_bf16_f32 v212, v206, v207
	v_cvt_pk_bf16_f32 v213, v208, v209
	s_nop 0
	global_store_dwordx4 v[138:139], v[210:213], off
	s_nop 1
	v_lshl_add_u64 v[138:139], v[138:139], 0, s[16:17]
	v_pk_mul_f32 v[216:217], v[110:111], s[14:15] op_sel_hi:[1,0]
	v_pk_mul_f32 v[218:219], v[112:113], s[14:15] op_sel_hi:[1,0]
	v_pk_mul_f32 v[220:221], v[106:107], s[14:15] op_sel_hi:[1,0]
	v_pk_mul_f32 v[222:223], v[108:109], s[14:15] op_sel_hi:[1,0]
	v_exp_f32_e32 v216, v216
	v_exp_f32_e32 v217, v217
	v_exp_f32_e32 v218, v218
	v_exp_f32_e32 v219, v219
	v_exp_f32_e32 v220, v220
	v_exp_f32_e32 v221, v221
	v_exp_f32_e32 v222, v222
	v_exp_f32_e32 v223, v223
	v_pk_add_f32 v[216:217], v[216:217], s[42:43] op_sel_hi:[1,0]
	v_pk_add_f32 v[218:219], v[218:219], s[42:43] op_sel_hi:[1,0]
	v_pk_add_f32 v[220:221], v[220:221], s[42:43] op_sel_hi:[1,0]
	v_pk_add_f32 v[222:223], v[222:223], s[42:43] op_sel_hi:[1,0]
	v_rcp_f32_e32 v216, v216
	v_rcp_f32_e32 v217, v217
	v_rcp_f32_e32 v218, v218
	v_rcp_f32_e32 v219, v219
	v_rcp_f32_e32 v220, v220
	v_rcp_f32_e32 v221, v221
	v_rcp_f32_e32 v222, v222
	v_rcp_f32_e32 v223, v223
	v_pk_mul_f32 v[216:217], v[110:111], v[216:217]
	v_pk_mul_f32 v[218:219], v[112:113], v[218:219]
	v_pk_mul_f32 v[220:221], v[106:107], v[220:221]
	v_pk_mul_f32 v[222:223], v[108:109], v[222:223]
	v_pk_mul_f32 v[216:217], v[216:217], v[102:103]
	v_pk_mul_f32 v[218:219], v[218:219], v[104:105]
	v_pk_mul_f32 v[220:221], v[220:221], v[98:99]
	v_pk_mul_f32 v[222:223], v[222:223], v[100:101]
	v_cvt_pk_bf16_f32 v224, v216, v217
	v_cvt_pk_bf16_f32 v225, v218, v219
	v_cvt_pk_bf16_f32 v226, v220, v221
	v_cvt_pk_bf16_f32 v227, v222, v223
	s_nop 0
	global_store_dwordx4 v[138:139], v[224:227], off
	s_nop 1
	v_lshl_add_u64 v[138:139], v[138:139], 0, s[16:17]
	v_pk_mul_f32 v[202:203], v[94:95], s[14:15] op_sel_hi:[1,0]
	v_pk_mul_f32 v[204:205], v[96:97], s[14:15] op_sel_hi:[1,0]
	v_pk_mul_f32 v[206:207], v[90:91], s[14:15] op_sel_hi:[1,0]
	v_pk_mul_f32 v[208:209], v[92:93], s[14:15] op_sel_hi:[1,0]
	v_exp_f32_e32 v202, v202
	v_exp_f32_e32 v203, v203
	v_exp_f32_e32 v204, v204
	v_exp_f32_e32 v205, v205
	v_exp_f32_e32 v206, v206
	v_exp_f32_e32 v207, v207
	v_exp_f32_e32 v208, v208
	v_exp_f32_e32 v209, v209
	v_pk_add_f32 v[202:203], v[202:203], s[42:43] op_sel_hi:[1,0]
	v_pk_add_f32 v[204:205], v[204:205], s[42:43] op_sel_hi:[1,0]
	v_pk_add_f32 v[206:207], v[206:207], s[42:43] op_sel_hi:[1,0]
	v_pk_add_f32 v[208:209], v[208:209], s[42:43] op_sel_hi:[1,0]
	v_rcp_f32_e32 v202, v202
	v_rcp_f32_e32 v203, v203
	v_rcp_f32_e32 v204, v204
	v_rcp_f32_e32 v205, v205
	v_rcp_f32_e32 v206, v206
	v_rcp_f32_e32 v207, v207
	v_rcp_f32_e32 v208, v208
	v_rcp_f32_e32 v209, v209
	v_pk_mul_f32 v[202:203], v[94:95], v[202:203]
	v_pk_mul_f32 v[204:205], v[96:97], v[204:205]
	v_pk_mul_f32 v[206:207], v[90:91], v[206:207]
	v_pk_mul_f32 v[208:209], v[92:93], v[208:209]
	v_pk_mul_f32 v[202:203], v[202:203], v[86:87]
	v_pk_mul_f32 v[204:205], v[204:205], v[88:89]
	v_pk_mul_f32 v[206:207], v[206:207], v[82:83]
	v_pk_mul_f32 v[208:209], v[208:209], v[84:85]
	v_cvt_pk_bf16_f32 v210, v202, v203
	v_cvt_pk_bf16_f32 v211, v204, v205
	v_cvt_pk_bf16_f32 v212, v206, v207
	v_cvt_pk_bf16_f32 v213, v208, v209
	s_nop 0
	global_store_dwordx4 v[138:139], v[210:213], off
	s_nop 1
	v_lshl_add_u64 v[138:139], v[138:139], 0, s[16:17]
	v_pk_mul_f32 v[216:217], v[78:79], s[14:15] op_sel_hi:[1,0]
	v_pk_mul_f32 v[218:219], v[80:81], s[14:15] op_sel_hi:[1,0]
	v_pk_mul_f32 v[220:221], v[74:75], s[14:15] op_sel_hi:[1,0]
	v_pk_mul_f32 v[222:223], v[76:77], s[14:15] op_sel_hi:[1,0]
	v_exp_f32_e32 v216, v216
	v_exp_f32_e32 v217, v217
	v_exp_f32_e32 v218, v218
	v_exp_f32_e32 v219, v219
	v_exp_f32_e32 v220, v220
	v_exp_f32_e32 v221, v221
; __device__ __forceinline__ unsigned cvt_pk_bf16(float lo, float hi) { unsigned r; asm volatile("v_cvt_pk_bf16_f32 %0, %1, %2" : "=v"(r) : "v"(lo), "v"(hi)); return r; }
;     static __device__ __forceinline__ float sw(float g, float up) { return g * __builtin_amdgcn_rcpf(1.0f + __builtin_amdgcn_exp2f(-1.4426950408889634f * g)) * up; }
;     __device__ __forceinline__ void operator()(const f32x4 (&acc)[2][2][4][2], const Unit& u, int wr, int wc, int fr, int fq) const {
;     ...
;         for (int ai = 0; ai < 2; ++ai)
; #pragma unroll
;             for (int m = 0; m < 4; ++m) { bf16_t* rowp = Hout + (size_t)(row0 + ai * HALF + m * 16) * ldc + col0;
;                 const f32x4 g0 = acc[ai][0][m][0], g1 = acc[ai][0][m][1], u0 = acc[ai][1][m][0], u1 = acc[ai][1][m][1];
;                 u32x4 w; w.x = cvt_pk_bf16(sw(g0[0], u0[0]), sw(g0[1], u0[1])); w.y = cvt_pk_bf16(sw(g0[2], u0[2]), sw(g0[3], u0[3]));
;                 w.z = cvt_pk_bf16(sw(g1[0], u1[0]), sw(g1[1], u1[1])); w.w = cvt_pk_bf16(sw(g1[2], u1[2]), sw(g1[3], u1[3]));
;                 *(u32x4*)rowp = w; }
	v_exp_f32_e32 v222, v222
	v_exp_f32_e32 v223, v223
	v_pk_add_f32 v[216:217], v[216:217], s[42:43] op_sel_hi:[1,0]
	v_pk_add_f32 v[218:219], v[218:219], s[42:43] op_sel_hi:[1,0]
	v_pk_add_f32 v[220:221], v[220:221], s[42:43] op_sel_hi:[1,0]
	v_pk_add_f32 v[222:223], v[222:223], s[42:43] op_sel_hi:[1,0]
	v_rcp_f32_e32 v216, v216
	v_rcp_f32_e32 v217, v217
	v_rcp_f32_e32 v218, v218
	v_rcp_f32_e32 v219, v219
	v_rcp_f32_e32 v220, v220
	v_rcp_f32_e32 v221, v221
	v_rcp_f32_e32 v222, v222
	v_rcp_f32_e32 v223, v223
	v_pk_mul_f32 v[216:217], v[78:79], v[216:217]
	v_pk_mul_f32 v[218:219], v[80:81], v[218:219]
	v_pk_mul_f32 v[220:221], v[74:75], v[220:221]
	v_pk_mul_f32 v[222:223], v[76:77], v[222:223]
	v_pk_mul_f32 v[216:217], v[216:217], v[70:71]
	v_pk_mul_f32 v[218:219], v[218:219], v[72:73]
	v_pk_mul_f32 v[220:221], v[220:221], v[66:67]
	v_pk_mul_f32 v[222:223], v[222:223], v[68:69]
	v_cvt_pk_bf16_f32 v224, v216, v217
	v_cvt_pk_bf16_f32 v225, v218, v219
	v_cvt_pk_bf16_f32 v226, v220, v221
	v_cvt_pk_bf16_f32 v227, v222, v223
	s_nop 0
	global_store_dwordx4 v[138:139], v[224:227], off
	s_nop 1
	s_mov_b32 s16, 0xdc000
	v_lshl_add_u64 v[138:139], v[138:139], 0, s[16:17]
	s_mov_b32 s16, 0x2c000
	v_pk_mul_f32 v[202:203], v[62:63], s[14:15] op_sel_hi:[1,0]
	v_pk_mul_f32 v[204:205], v[64:65], s[14:15] op_sel_hi:[1,0]
	v_pk_mul_f32 v[206:207], v[58:59], s[14:15] op_sel_hi:[1,0]
	v_pk_mul_f32 v[208:209], v[60:61], s[14:15] op_sel_hi:[1,0]
	v_exp_f32_e32 v202, v202
	v_exp_f32_e32 v203, v203
	v_exp_f32_e32 v204, v204
	v_exp_f32_e32 v205, v205
	v_exp_f32_e32 v206, v206
	v_exp_f32_e32 v207, v207
	v_exp_f32_e32 v208, v208
	v_exp_f32_e32 v209, v209
	v_pk_add_f32 v[202:203], v[202:203], s[42:43] op_sel_hi:[1,0]
	v_pk_add_f32 v[204:205], v[204:205], s[42:43] op_sel_hi:[1,0]
	v_pk_add_f32 v[206:207], v[206:207], s[42:43] op_sel_hi:[1,0]
	v_pk_add_f32 v[208:209], v[208:209], s[42:43] op_sel_hi:[1,0]
	v_rcp_f32_e32 v202, v202
	v_rcp_f32_e32 v203, v203
	v_rcp_f32_e32 v204, v204
	v_rcp_f32_e32 v205, v205
	v_rcp_f32_e32 v206, v206
	v_rcp_f32_e32 v207, v207
	v_rcp_f32_e32 v208, v208
	v_rcp_f32_e32 v209, v209
	v_pk_mul_f32 v[202:203], v[62:63], v[202:203]
	v_pk_mul_f32 v[204:205], v[64:65], v[204:205]
	v_pk_mul_f32 v[206:207], v[58:59], v[206:207]
	v_pk_mul_f32 v[208:209], v[60:61], v[208:209]
	v_pk_mul_f32 v[202:203], v[202:203], v[54:55]
	v_pk_mul_f32 v[204:205], v[204:205], v[56:57]
	v_pk_mul_f32 v[206:207], v[206:207], v[50:51]
	v_pk_mul_f32 v[208:209], v[208:209], v[52:53]
	v_cvt_pk_bf16_f32 v210, v202, v203
	v_cvt_pk_bf16_f32 v211, v204, v205
	v_cvt_pk_bf16_f32 v212, v206, v207
	v_cvt_pk_bf16_f32 v213, v208, v209
	s_nop 0
	global_store_dwordx4 v[138:139], v[210:213], off
	s_nop 1
	v_lshl_add_u64 v[138:139], v[138:139], 0, s[16:17]
	v_pk_mul_f32 v[216:217], v[46:47], s[14:15] op_sel_hi:[1,0]
	v_pk_mul_f32 v[218:219], v[48:49], s[14:15] op_sel_hi:[1,0]
	v_pk_mul_f32 v[220:221], v[42:43], s[14:15] op_sel_hi:[1,0]
	v_pk_mul_f32 v[222:223], v[44:45], s[14:15] op_sel_hi:[1,0]
	v_exp_f32_e32 v216, v216
	v_exp_f32_e32 v217, v217
	v_exp_f32_e32 v218, v218
	v_exp_f32_e32 v219, v219
	v_exp_f32_e32 v220, v220
	v_exp_f32_e32 v221, v221
	v_exp_f32_e32 v222, v222
	v_exp_f32_e32 v223, v223
	v_pk_add_f32 v[216:217], v[216:217], s[42:43] op_sel_hi:[1,0]
	v_pk_add_f32 v[218:219], v[218:219], s[42:43] op_sel_hi:[1,0]
	v_pk_add_f32 v[220:221], v[220:221], s[42:43] op_sel_hi:[1,0]
	v_pk_add_f32 v[222:223], v[222:223], s[42:43] op_sel_hi:[1,0]
	v_rcp_f32_e32 v216, v216
	v_rcp_f32_e32 v217, v217
	v_rcp_f32_e32 v218, v218
	v_rcp_f32_e32 v219, v219
	v_rcp_f32_e32 v220, v220
	v_rcp_f32_e32 v221, v221
	v_rcp_f32_e32 v222, v222
	v_rcp_f32_e32 v223, v223
; __device__ __forceinline__ unsigned cvt_pk_bf16(float lo, float hi) { unsigned r; asm volatile("v_cvt_pk_bf16_f32 %0, %1, %2" : "=v"(r) : "v"(lo), "v"(hi)); return r; }
;     static __device__ __forceinline__ float sw(float g, float up) { return g * __builtin_amdgcn_rcpf(1.0f + __builtin_amdgcn_exp2f(-1.4426950408889634f * g)) * up; }
;     __device__ __forceinline__ void operator()(const f32x4 (&acc)[2][2][4][2], const Unit& u, int wr, int wc, int fr, int fq) const {
;     ...
;         for (int ai = 0; ai < 2; ++ai)
; #pragma unroll
;             for (int m = 0; m < 4; ++m) { bf16_t* rowp = Hout + (size_t)(row0 + ai * HALF + m * 16) * ldc + col0;
;                 const f32x4 g0 = acc[ai][0][m][0], g1 = acc[ai][0][m][1], u0 = acc[ai][1][m][0], u1 = acc[ai][1][m][1];
;                 u32x4 w; w.x = cvt_pk_bf16(sw(g0[0], u0[0]), sw(g0[1], u0[1])); w.y = cvt_pk_bf16(sw(g0[2], u0[2]), sw(g0[3], u0[3]));
;                 w.z = cvt_pk_bf16(sw(g1[0], u1[0]), sw(g1[1], u1[1])); w.w = cvt_pk_bf16(sw(g1[2], u1[2]), sw(g1[3], u1[3]));
;                 *(u32x4*)rowp = w; }
	v_pk_mul_f32 v[216:217], v[46:47], v[216:217]
	v_pk_mul_f32 v[218:219], v[48:49], v[218:219]
	v_pk_mul_f32 v[220:221], v[42:43], v[220:221]
	v_pk_mul_f32 v[222:223], v[44:45], v[222:223]
	v_pk_mul_f32 v[216:217], v[216:217], v[38:39]
	v_pk_mul_f32 v[218:219], v[218:219], v[40:41]
	v_pk_mul_f32 v[220:221], v[220:221], v[34:35]
	v_pk_mul_f32 v[222:223], v[222:223], v[36:37]
	v_cvt_pk_bf16_f32 v224, v216, v217
	v_cvt_pk_bf16_f32 v225, v218, v219
	v_cvt_pk_bf16_f32 v226, v220, v221
	v_cvt_pk_bf16_f32 v227, v222, v223
	s_nop 0
	global_store_dwordx4 v[138:139], v[224:227], off
	s_nop 1
	v_lshl_add_u64 v[138:139], v[138:139], 0, s[16:17]
	v_pk_mul_f32 v[202:203], v[30:31], s[14:15] op_sel_hi:[1,0]
	v_pk_mul_f32 v[204:205], v[32:33], s[14:15] op_sel_hi:[1,0]
	v_pk_mul_f32 v[206:207], v[26:27], s[14:15] op_sel_hi:[1,0]
	v_pk_mul_f32 v[208:209], v[28:29], s[14:15] op_sel_hi:[1,0]
	v_exp_f32_e32 v202, v202
	v_exp_f32_e32 v203, v203
	v_exp_f32_e32 v204, v204
	v_exp_f32_e32 v205, v205
	v_exp_f32_e32 v206, v206
	v_exp_f32_e32 v207, v207
	v_exp_f32_e32 v208, v208
	v_exp_f32_e32 v209, v209
	v_pk_add_f32 v[202:203], v[202:203], s[42:43] op_sel_hi:[1,0]
	v_pk_add_f32 v[204:205], v[204:205], s[42:43] op_sel_hi:[1,0]
	v_pk_add_f32 v[206:207], v[206:207], s[42:43] op_sel_hi:[1,0]
	v_pk_add_f32 v[208:209], v[208:209], s[42:43] op_sel_hi:[1,0]
	v_rcp_f32_e32 v202, v202
	v_rcp_f32_e32 v203, v203
	v_rcp_f32_e32 v204, v204
	v_rcp_f32_e32 v205, v205
	v_rcp_f32_e32 v206, v206
	v_rcp_f32_e32 v207, v207
	v_rcp_f32_e32 v208, v208
	v_rcp_f32_e32 v209, v209
	v_pk_mul_f32 v[202:203], v[30:31], v[202:203]
	v_pk_mul_f32 v[204:205], v[32:33], v[204:205]
	v_pk_mul_f32 v[206:207], v[26:27], v[206:207]
	v_pk_mul_f32 v[208:209], v[28:29], v[208:209]
	v_pk_mul_f32 v[202:203], v[202:203], v[22:23]
	v_pk_mul_f32 v[204:205], v[204:205], v[24:25]
	v_pk_mul_f32 v[206:207], v[206:207], v[18:19]
	v_pk_mul_f32 v[208:209], v[208:209], v[20:21]
	v_cvt_pk_bf16_f32 v210, v202, v203
	v_cvt_pk_bf16_f32 v211, v204, v205
	v_cvt_pk_bf16_f32 v212, v206, v207
	v_cvt_pk_bf16_f32 v213, v208, v209
	s_nop 0
	global_store_dwordx4 v[138:139], v[210:213], off
	s_nop 1
	v_lshl_add_u64 v[138:139], v[138:139], 0, s[16:17]
	v_pk_mul_f32 v[216:217], v[14:15], s[14:15] op_sel_hi:[1,0]
	v_pk_mul_f32 v[218:219], v[16:17], s[14:15] op_sel_hi:[1,0]
	v_pk_mul_f32 v[220:221], v[10:11], s[14:15] op_sel_hi:[1,0]
	v_pk_mul_f32 v[222:223], v[12:13], s[14:15] op_sel_hi:[1,0]
	v_exp_f32_e32 v216, v216
	v_exp_f32_e32 v217, v217
	v_exp_f32_e32 v218, v218
	v_exp_f32_e32 v219, v219
	v_exp_f32_e32 v220, v220
	v_exp_f32_e32 v221, v221
	v_exp_f32_e32 v222, v222
	v_exp_f32_e32 v223, v223
	v_pk_add_f32 v[216:217], v[216:217], s[42:43] op_sel_hi:[1,0]
	v_pk_add_f32 v[218:219], v[218:219], s[42:43] op_sel_hi:[1,0]
	v_pk_add_f32 v[220:221], v[220:221], s[42:43] op_sel_hi:[1,0]
	v_pk_add_f32 v[222:223], v[222:223], s[42:43] op_sel_hi:[1,0]
	v_rcp_f32_e32 v216, v216
	v_rcp_f32_e32 v217, v217
	v_rcp_f32_e32 v218, v218
	v_rcp_f32_e32 v219, v219
	v_rcp_f32_e32 v220, v220
	v_rcp_f32_e32 v221, v221
	v_rcp_f32_e32 v222, v222
	v_rcp_f32_e32 v223, v223
	v_pk_mul_f32 v[216:217], v[14:15], v[216:217]
	v_pk_mul_f32 v[218:219], v[16:17], v[218:219]
	v_pk_mul_f32 v[220:221], v[10:11], v[220:221]
	v_pk_mul_f32 v[222:223], v[12:13], v[222:223]
	v_pk_mul_f32 v[216:217], v[216:217], v[6:7]
	v_pk_mul_f32 v[218:219], v[218:219], v[8:9]
	v_pk_mul_f32 v[220:221], v[220:221], v[2:3]
	v_pk_mul_f32 v[222:223], v[222:223], v[4:5]
	v_cvt_pk_bf16_f32 v224, v216, v217
	v_cvt_pk_bf16_f32 v225, v218, v219
	v_cvt_pk_bf16_f32 v226, v220, v221
	v_cvt_pk_bf16_f32 v227, v222, v223
	s_nop 0
	global_store_dwordx4 v[138:139], v[224:227], off
	s_nop 1
	s_mov_b64 s[12:13], 0
